# v2: hyena neighbour loads batched + phase-0 SiLU staging loads batched (18 in flight)
# speedup vs baseline: 1.0204x; 1.0089x over previous
.LBB0_34:
	v_mov_b32_e32 v55, v234
	s_nop 0
	v_cmp_lt_i32_e32 vcc, s69, v55
	v_lshlrev_b32_e32 v4, 2, v55
	s_and_saveexec_b64 s[8:9], vcc
	s_xor_b64 s[8:9], exec, s[8:9]
	v_lshlrev_b32_e32 v4, 2, v55
	s_andn2_saveexec_b64 s[8:9], s[8:9]
	s_cbranch_execz .LBB0_45
	v_add_u32_e32 v5, 0, v4
	global_load_dword v84, v4, s[18:19]
	global_load_dword v85, v4, s[18:19] offset:2048
	global_load_dword v86, v4, s[16:17]
	global_load_dword v87, v4, s[16:17] offset:2048
	s_add_u32 s10, s16, 0x1000
	s_addc_u32 s11, s17, 0
	global_load_dword v88, v4, s[10:11]
	global_load_dword v89, v4, s[10:11] offset:2048
	s_add_u32 s10, s10, 0x1000
	s_addc_u32 s11, s11, 0
	global_load_dword v90, v4, s[10:11]
	global_load_dword v91, v4, s[10:11] offset:2048
	s_add_u32 s10, s10, 0x1000
	s_addc_u32 s11, s11, 0
	global_load_dword v92, v4, s[10:11]
	global_load_dword v93, v4, s[10:11] offset:2048
	s_add_u32 s10, s10, 0x1000
	s_addc_u32 s11, s11, 0
	global_load_dword v94, v4, s[10:11]
	global_load_dword v95, v4, s[10:11] offset:2048
	s_add_u32 s10, s10, 0x1000
	s_addc_u32 s11, s11, 0
	global_load_dword v96, v4, s[10:11]
	global_load_dword v97, v4, s[10:11] offset:2048
	s_add_u32 s10, s10, 0x1000
	s_addc_u32 s11, s11, 0
	global_load_dword v98, v4, s[10:11]
	global_load_dword v99, v4, s[10:11] offset:2048
	s_add_u32 s10, s10, 0x1000
	s_addc_u32 s11, s11, 0
	global_load_dword v100, v4, s[10:11]
	global_load_dword v101, v4, s[10:11] offset:2048
	s_waitcnt vmcnt(17)
	v_mul_f32_e32 v102, 0xbfb8aa3b, v84
	v_exp_f32_e32 v102, v102
	s_nop 0
	v_add_f32_e32 v102, 1.0, v102
	v_rcp_f32_e32 v102, v102
	s_nop 0
	v_mul_f32_e32 v84, v84, v102
	ds_write_b32 v5, v84 offset:0
	s_waitcnt vmcnt(16)
	v_mul_f32_e32 v102, 0xbfb8aa3b, v85
	v_exp_f32_e32 v102, v102
	s_nop 0
	v_add_f32_e32 v102, 1.0, v102
	v_rcp_f32_e32 v102, v102
	s_nop 0
	v_mul_f32_e32 v85, v85, v102
	ds_write_b32 v5, v85 offset:2048
	s_waitcnt vmcnt(15)
	v_mul_f32_e32 v102, 0xbfb8aa3b, v86
	v_exp_f32_e32 v102, v102
	s_nop 0
	v_add_f32_e32 v102, 1.0, v102
	v_rcp_f32_e32 v102, v102
	s_nop 0
	v_mul_f32_e32 v86, v86, v102
	ds_write_b32 v5, v86 offset:4096
	s_waitcnt vmcnt(14)
	v_mul_f32_e32 v102, 0xbfb8aa3b, v87
	v_exp_f32_e32 v102, v102
	s_nop 0
	v_add_f32_e32 v102, 1.0, v102
	v_rcp_f32_e32 v102, v102
	s_nop 0
	v_mul_f32_e32 v87, v87, v102
	ds_write_b32 v5, v87 offset:6144
	s_waitcnt vmcnt(13)
	v_mul_f32_e32 v102, 0xbfb8aa3b, v88
	v_exp_f32_e32 v102, v102
	s_nop 0
	v_add_f32_e32 v102, 1.0, v102
	v_rcp_f32_e32 v102, v102
	s_nop 0
	v_mul_f32_e32 v88, v88, v102
	ds_write_b32 v5, v88 offset:8192
	s_waitcnt vmcnt(12)
	v_mul_f32_e32 v102, 0xbfb8aa3b, v89
	v_exp_f32_e32 v102, v102
	s_nop 0
	v_add_f32_e32 v102, 1.0, v102
	v_rcp_f32_e32 v102, v102
	s_nop 0
	v_mul_f32_e32 v89, v89, v102
	ds_write_b32 v5, v89 offset:10240
	s_waitcnt vmcnt(11)
	v_mul_f32_e32 v102, 0xbfb8aa3b, v90
	v_exp_f32_e32 v102, v102
	s_nop 0
	v_add_f32_e32 v102, 1.0, v102
	v_rcp_f32_e32 v102, v102
	s_nop 0
	v_mul_f32_e32 v90, v90, v102
	ds_write_b32 v5, v90 offset:12288
	s_waitcnt vmcnt(10)
	v_mul_f32_e32 v102, 0xbfb8aa3b, v91
	v_exp_f32_e32 v102, v102
	s_nop 0
	v_add_f32_e32 v102, 1.0, v102
	v_rcp_f32_e32 v102, v102
	s_nop 0
	v_mul_f32_e32 v91, v91, v102
	ds_write_b32 v5, v91 offset:14336
	s_waitcnt vmcnt(9)
	v_mul_f32_e32 v102, 0xbfb8aa3b, v92
	v_exp_f32_e32 v102, v102
	s_nop 0
	v_add_f32_e32 v102, 1.0, v102
	v_rcp_f32_e32 v102, v102
	s_nop 0
	v_mul_f32_e32 v92, v92, v102
	ds_write_b32 v5, v92 offset:16384
	s_waitcnt vmcnt(8)
	v_mul_f32_e32 v102, 0xbfb8aa3b, v93
	v_exp_f32_e32 v102, v102
	s_nop 0
	v_add_f32_e32 v102, 1.0, v102
	v_rcp_f32_e32 v102, v102
	s_nop 0
	v_mul_f32_e32 v93, v93, v102
	ds_write_b32 v5, v93 offset:18432
	s_waitcnt vmcnt(7)
	v_mul_f32_e32 v102, 0xbfb8aa3b, v94
	v_exp_f32_e32 v102, v102
	s_nop 0
	v_add_f32_e32 v102, 1.0, v102
	v_rcp_f32_e32 v102, v102
	s_nop 0
	v_mul_f32_e32 v94, v94, v102
	ds_write_b32 v5, v94 offset:20480
	s_waitcnt vmcnt(6)
	v_mul_f32_e32 v102, 0xbfb8aa3b, v95
	v_exp_f32_e32 v102, v102
	s_nop 0
	v_add_f32_e32 v102, 1.0, v102
	v_rcp_f32_e32 v102, v102
	s_nop 0
	v_mul_f32_e32 v95, v95, v102
	ds_write_b32 v5, v95 offset:22528
	s_waitcnt vmcnt(5)
	v_mul_f32_e32 v102, 0xbfb8aa3b, v96
	v_exp_f32_e32 v102, v102
	s_nop 0
	v_add_f32_e32 v102, 1.0, v102
	v_rcp_f32_e32 v102, v102
	s_nop 0
	v_mul_f32_e32 v96, v96, v102
	ds_write_b32 v5, v96 offset:24576
	s_waitcnt vmcnt(4)
	v_mul_f32_e32 v102, 0xbfb8aa3b, v97
	v_exp_f32_e32 v102, v102
	s_nop 0
	v_add_f32_e32 v102, 1.0, v102
	v_rcp_f32_e32 v102, v102
	s_nop 0
	v_mul_f32_e32 v97, v97, v102
	ds_write_b32 v5, v97 offset:26624
	s_waitcnt vmcnt(3)
	v_mul_f32_e32 v102, 0xbfb8aa3b, v98
	v_exp_f32_e32 v102, v102
	s_nop 0
	v_add_f32_e32 v102, 1.0, v102
	v_rcp_f32_e32 v102, v102
	s_nop 0
	v_mul_f32_e32 v98, v98, v102
	ds_write_b32 v5, v98 offset:28672
	s_waitcnt vmcnt(2)
	v_mul_f32_e32 v102, 0xbfb8aa3b, v99
	v_exp_f32_e32 v102, v102
	s_nop 0
	v_add_f32_e32 v102, 1.0, v102
	v_rcp_f32_e32 v102, v102
	s_nop 0
	v_mul_f32_e32 v99, v99, v102
	ds_write_b32 v5, v99 offset:30720
	s_waitcnt vmcnt(1)
	v_mul_f32_e32 v102, 0xbfb8aa3b, v100
	v_exp_f32_e32 v102, v102
	s_nop 0
	v_add_f32_e32 v102, 1.0, v102
	v_rcp_f32_e32 v102, v102
	s_nop 0
	v_mul_f32_e32 v100, v100, v102
	ds_write_b32 v5, v100 offset:32768
	s_waitcnt vmcnt(0)
	v_mul_f32_e32 v102, 0xbfb8aa3b, v101
	v_exp_f32_e32 v102, v102
	s_nop 0
	v_add_f32_e32 v102, 1.0, v102
	v_rcp_f32_e32 v102, v102
	s_nop 0
	v_mul_f32_e32 v101, v101, v102
	ds_write_b32 v5, v101 offset:34816
	s_branch .LBB0_45
.LBB0_43:
	s_cbranch_execnz .LBB0_9
	s_branch .LBB0_34
.LBB0_45:
	s_or_b64 exec, exec, s[8:9]
	s_lshl_b32 s8, s75, 5
	s_ashr_i32 s9, s8, 31
	s_lshl_b64 s[10:11], s[8:9], 2
	s_add_u32 s10, s20, s10
	v_and_b32_e32 v2, 28, v4
	s_addc_u32 s11, s21, s11
	v_lshlrev_b32_e32 v12, 2, v2
	v_ashrrev_i32_e32 v112, 3, v55
	v_lshl_add_u64 v[64:65], s[10:11], 0, v[12:13]
	v_mad_i64_i32 v[2:3], s[10:11], v112, s72, v[64:65]
	s_waitcnt lgkmcnt(0)
	s_barrier
	global_load_dwordx4 v[6:9], v[2:3], off
	v_add_u32_e32 v2, 64, v112
	v_mad_i64_i32 v[2:3], s[10:11], v2, s72, v[64:65]
	global_load_dwordx4 v[2:5], v[2:3], off
	v_add_u32_e32 v72, 0x80, v112
	v_lshl_add_u32 v12, v112, 2, 0
	v_add_u32_e32 v76, 0xc0, v112
	v_mad_i64_i32 v[72:73], s[10:11], v72, s72, v[64:65]
	ds_read2st64_b32 v[80:81], v12 offset1:1
	ds_read2st64_b32 v[84:85], v12 offset0:2 offset1:3
	ds_read2st64_b32 v[86:87], v12 offset0:4 offset1:5
	ds_read2st64_b32 v[66:67], v12 offset0:6 offset1:7
	ds_read2st64_b32 v[82:83], v12 offset0:16 offset1:17
	ds_read2st64_b32 v[88:89], v12 offset0:18 offset1:19
	ds_read2st64_b32 v[90:91], v12 offset0:20 offset1:21
	ds_read2st64_b32 v[68:69], v12 offset0:22 offset1:23
	ds_read2st64_b32 v[92:93], v12 offset0:32 offset1:33
	ds_read2st64_b32 v[94:95], v12 offset0:34 offset1:35
	ds_read2st64_b32 v[96:97], v12 offset0:36 offset1:37
	ds_read2st64_b32 v[70:71], v12 offset0:38 offset1:39
	global_load_dwordx4 v[72:75], v[72:73], off
	v_mad_i64_i32 v[76:77], s[10:11], v76, s72, v[64:65]
	ds_read2st64_b32 v[98:99], v12 offset0:48 offset1:49
	ds_read2st64_b32 v[100:101], v12 offset0:50 offset1:51
	ds_read2st64_b32 v[102:103], v12 offset0:52 offset1:53
	ds_read2st64_b32 v[106:107], v12 offset0:54 offset1:55
	ds_read2st64_b32 v[104:105], v12 offset0:64 offset1:65
	ds_read2st64_b32 v[108:109], v12 offset0:66 offset1:67
	ds_read2st64_b32 v[110:111], v12 offset0:68 offset1:69
	ds_read2st64_b32 v[118:119], v12 offset0:70 offset1:71
	ds_read2st64_b32 v[114:115], v12 offset0:80 offset1:81
	ds_read2st64_b32 v[116:117], v12 offset0:82 offset1:83
	ds_read2st64_b32 v[120:121], v12 offset0:84 offset1:85
	ds_read2st64_b32 v[122:123], v12 offset0:86 offset1:87
	ds_read2st64_b32 v[124:125], v12 offset0:96 offset1:97
	ds_read2st64_b32 v[126:127], v12 offset0:98 offset1:99
	ds_read2st64_b32 v[140:141], v12 offset0:100 offset1:101
	ds_read2st64_b32 v[142:143], v12 offset0:102 offset1:103
	global_load_dwordx4 v[76:79], v[76:77], off
	ds_read2st64_b32 v[144:145], v12 offset0:112 offset1:113
	ds_read2st64_b32 v[146:147], v12 offset0:114 offset1:115
	ds_read2st64_b32 v[148:149], v12 offset0:116 offset1:117
	ds_read2st64_b32 v[150:151], v12 offset0:118 offset1:119
	ds_read2st64_b32 v[152:153], v12 offset0:128 offset1:129
	ds_read2st64_b32 v[154:155], v12 offset0:130 offset1:131
	ds_read2st64_b32 v[156:157], v12 offset0:132 offset1:133
	ds_read2st64_b32 v[158:159], v12 offset0:134 offset1:135
	v_add_u32_e32 v113, 0x100, v112
	s_waitcnt lgkmcnt(14)
	v_mov_b32_e32 v162, v81
	v_mov_b32_e32 v164, v83
	s_waitcnt vmcnt(3)
	v_pk_fma_f32 v[166:167], v[8:9], v[80:81], 0 op_sel_hi:[1,0,0]
	v_pk_fma_f32 v[80:81], v[6:7], v[80:81], 0 op_sel_hi:[1,0,0]
	v_pk_fma_f32 v[168:169], v[8:9], v[82:83], 0 op_sel_hi:[1,0,0]
	v_pk_fma_f32 v[82:83], v[6:7], v[82:83], 0 op_sel_hi:[1,0,0]
	v_pk_fma_f32 v[172:173], v[6:7], v[92:93], 0 op_sel_hi:[1,0,0]
	v_pk_fma_f32 v[176:177], v[6:7], v[98:99], 0 op_sel_hi:[1,0,0]
	v_pk_fma_f32 v[180:181], v[6:7], v[104:105], 0 op_sel_hi:[1,0,0]
	v_pk_fma_f32 v[184:185], v[6:7], v[114:115], 0 op_sel_hi:[1,0,0]
	s_waitcnt lgkmcnt(11)
	v_pk_fma_f32 v[188:189], v[6:7], v[124:125], 0 op_sel_hi:[1,0,0]
	s_waitcnt lgkmcnt(7)
	v_pk_fma_f32 v[192:193], v[6:7], v[144:145], 0 op_sel_hi:[1,0,0]
	s_waitcnt lgkmcnt(3)
	v_pk_fma_f32 v[196:197], v[6:7], v[152:153], 0 op_sel_hi:[1,0,0]
	v_mad_i64_i32 v[6:7], s[10:11], v113, s72, v[64:65]
	v_pk_fma_f32 v[170:171], v[8:9], v[92:93], 0 op_sel_hi:[1,0,0]
	v_pk_fma_f32 v[174:175], v[8:9], v[98:99], 0 op_sel_hi:[1,0,0]
	v_pk_fma_f32 v[178:179], v[8:9], v[104:105], 0 op_sel_hi:[1,0,0]
	v_pk_fma_f32 v[182:183], v[8:9], v[114:115], 0 op_sel_hi:[1,0,0]
	v_pk_fma_f32 v[186:187], v[8:9], v[124:125], 0 op_sel_hi:[1,0,0]
	v_pk_fma_f32 v[190:191], v[8:9], v[144:145], 0 op_sel_hi:[1,0,0]
	v_pk_fma_f32 v[194:195], v[8:9], v[152:153], 0 op_sel_hi:[1,0,0]
	global_load_dwordx4 v[6:9], v[6:7], off
	s_waitcnt vmcnt(3)
	v_pk_fma_f32 v[166:167], v[4:5], v[162:163], v[166:167] op_sel_hi:[1,0,1]
	v_pk_fma_f32 v[162:163], v[2:3], v[162:163], v[80:81] op_sel_hi:[1,0,1]
	v_mov_b32_e32 v80, v93
	v_pk_fma_f32 v[92:93], v[4:5], v[80:81], v[170:171] op_sel_hi:[1,0,1]
	v_pk_fma_f32 v[170:171], v[2:3], v[80:81], v[172:173] op_sel_hi:[1,0,1]
	v_mov_b32_e32 v80, v99
	v_pk_fma_f32 v[98:99], v[4:5], v[80:81], v[174:175] op_sel_hi:[1,0,1]
	v_pk_fma_f32 v[172:173], v[2:3], v[80:81], v[176:177] op_sel_hi:[1,0,1]
	v_mov_b32_e32 v80, v105
	v_pk_fma_f32 v[104:105], v[4:5], v[80:81], v[178:179] op_sel_hi:[1,0,1]
	v_pk_fma_f32 v[174:175], v[2:3], v[80:81], v[180:181] op_sel_hi:[1,0,1]
	v_mov_b32_e32 v80, v115
	v_pk_fma_f32 v[114:115], v[4:5], v[80:81], v[182:183] op_sel_hi:[1,0,1]
	v_pk_fma_f32 v[176:177], v[2:3], v[80:81], v[184:185] op_sel_hi:[1,0,1]
	v_mov_b32_e32 v80, v125
	v_pk_fma_f32 v[124:125], v[4:5], v[80:81], v[186:187] op_sel_hi:[1,0,1]
	v_pk_fma_f32 v[178:179], v[2:3], v[80:81], v[188:189] op_sel_hi:[1,0,1]
	v_mov_b32_e32 v80, v145
	v_pk_fma_f32 v[144:145], v[4:5], v[80:81], v[190:191] op_sel_hi:[1,0,1]
	v_pk_fma_f32 v[180:181], v[2:3], v[80:81], v[192:193] op_sel_hi:[1,0,1]
	v_add_u32_e32 v80, 0x140, v112
	v_mad_i64_i32 v[80:81], s[10:11], v80, s72, v[64:65]
	v_pk_fma_f32 v[168:169], v[4:5], v[164:165], v[168:169] op_sel_hi:[1,0,1]
	v_pk_fma_f32 v[164:165], v[2:3], v[164:165], v[82:83] op_sel_hi:[1,0,1]
	global_load_dwordx4 v[80:83], v[80:81], off
	v_mov_b32_e32 v152, v153
	v_pk_fma_f32 v[2:3], v[2:3], v[152:153], v[196:197] op_sel_hi:[1,0,1]
	v_pk_fma_f32 v[4:5], v[4:5], v[152:153], v[194:195] op_sel_hi:[1,0,1]
	s_waitcnt vmcnt(3)
	v_pk_fma_f32 v[152:153], v[74:75], v[84:85], v[166:167] op_sel_hi:[1,0,1]
	v_pk_fma_f32 v[162:163], v[72:73], v[84:85], v[162:163] op_sel_hi:[1,0,1]
	v_pk_fma_f32 v[166:167], v[74:75], v[88:89], v[168:169] op_sel_hi:[1,0,1]
	v_pk_fma_f32 v[164:165], v[72:73], v[88:89], v[164:165] op_sel_hi:[1,0,1]
	v_pk_fma_f32 v[168:169], v[72:73], v[94:95], v[170:171] op_sel_hi:[1,0,1]
	v_pk_fma_f32 v[170:171], v[72:73], v[100:101], v[172:173] op_sel_hi:[1,0,1]
	v_pk_fma_f32 v[172:173], v[72:73], v[108:109], v[174:175] op_sel_hi:[1,0,1]
	v_pk_fma_f32 v[174:175], v[72:73], v[116:117], v[176:177] op_sel_hi:[1,0,1]
	v_pk_fma_f32 v[176:177], v[72:73], v[126:127], v[178:179] op_sel_hi:[1,0,1]
	v_pk_fma_f32 v[178:179], v[72:73], v[146:147], v[180:181] op_sel_hi:[1,0,1]
	s_waitcnt lgkmcnt(2)
	v_pk_fma_f32 v[72:73], v[72:73], v[154:155], v[2:3] op_sel_hi:[1,0,1]
	v_mov_b32_e32 v2, v85
	s_waitcnt vmcnt(2)
	v_pk_fma_f32 v[84:85], v[78:79], v[2:3], v[152:153] op_sel_hi:[1,0,1]
	v_pk_fma_f32 v[152:153], v[76:77], v[2:3], v[162:163] op_sel_hi:[1,0,1]
	v_add_u32_e32 v2, 0x180, v112
	v_pk_fma_f32 v[114:115], v[74:75], v[116:117], v[114:115] op_sel_hi:[1,0,1]
	v_mov_b32_e32 v88, v89
	v_mad_i64_i32 v[2:3], s[10:11], v2, s72, v[64:65]
	v_mov_b32_e32 v116, v117
	v_add_u32_e32 v113, 0x1c0, v112
	v_pk_fma_f32 v[92:93], v[74:75], v[94:95], v[92:93] op_sel_hi:[1,0,1]
	v_pk_fma_f32 v[98:99], v[74:75], v[100:101], v[98:99] op_sel_hi:[1,0,1]
	v_pk_fma_f32 v[104:105], v[74:75], v[108:109], v[104:105] op_sel_hi:[1,0,1]
	v_pk_fma_f32 v[124:125], v[74:75], v[126:127], v[124:125] op_sel_hi:[1,0,1]
	v_pk_fma_f32 v[144:145], v[74:75], v[146:147], v[144:145] op_sel_hi:[1,0,1]
	v_pk_fma_f32 v[74:75], v[74:75], v[154:155], v[4:5] op_sel_hi:[1,0,1]
	global_load_dwordx4 v[2:5], v[2:3], off
	v_pk_fma_f32 v[162:163], v[78:79], v[88:89], v[166:167] op_sel_hi:[1,0,1]
	v_pk_fma_f32 v[88:89], v[76:77], v[88:89], v[164:165] op_sel_hi:[1,0,1]
	v_pk_fma_f32 v[164:165], v[78:79], v[116:117], v[114:115] op_sel_hi:[1,0,1]
	v_mad_i64_i32 v[114:115], s[10:11], v113, s72, v[64:65]
	v_pk_fma_f32 v[166:167], v[76:77], v[116:117], v[174:175] op_sel_hi:[1,0,1]
	global_load_dwordx4 v[114:117], v[114:115], off
	v_mov_b32_e32 v94, v95
	v_mov_b32_e32 v100, v101
	v_mov_b32_e32 v108, v109
	v_mov_b32_e32 v126, v127
	v_mov_b32_e32 v146, v147
	v_mov_b32_e32 v154, v155
	v_pk_fma_f32 v[92:93], v[78:79], v[94:95], v[92:93] op_sel_hi:[1,0,1]
	v_pk_fma_f32 v[94:95], v[76:77], v[94:95], v[168:169] op_sel_hi:[1,0,1]
	v_pk_fma_f32 v[98:99], v[78:79], v[100:101], v[98:99] op_sel_hi:[1,0,1]
	v_pk_fma_f32 v[100:101], v[76:77], v[100:101], v[170:171] op_sel_hi:[1,0,1]
	v_pk_fma_f32 v[104:105], v[78:79], v[108:109], v[104:105] op_sel_hi:[1,0,1]
	v_pk_fma_f32 v[108:109], v[76:77], v[108:109], v[172:173] op_sel_hi:[1,0,1]
	v_pk_fma_f32 v[124:125], v[78:79], v[126:127], v[124:125] op_sel_hi:[1,0,1]
	v_pk_fma_f32 v[126:127], v[76:77], v[126:127], v[176:177] op_sel_hi:[1,0,1]
	v_pk_fma_f32 v[144:145], v[78:79], v[146:147], v[144:145] op_sel_hi:[1,0,1]
	v_pk_fma_f32 v[146:147], v[76:77], v[146:147], v[178:179] op_sel_hi:[1,0,1]
	v_pk_fma_f32 v[72:73], v[76:77], v[154:155], v[72:73] op_sel_hi:[1,0,1]
	v_pk_fma_f32 v[74:75], v[78:79], v[154:155], v[74:75] op_sel_hi:[1,0,1]
	s_waitcnt vmcnt(3)
	v_pk_fma_f32 v[78:79], v[6:7], v[86:87], v[152:153] op_sel_hi:[1,0,1]
	v_pk_fma_f32 v[88:89], v[6:7], v[90:91], v[88:89] op_sel_hi:[1,0,1]
	v_pk_fma_f32 v[94:95], v[6:7], v[96:97], v[94:95] op_sel_hi:[1,0,1]
	v_pk_fma_f32 v[100:101], v[6:7], v[102:103], v[100:101] op_sel_hi:[1,0,1]
	v_pk_fma_f32 v[108:109], v[6:7], v[110:111], v[108:109] op_sel_hi:[1,0,1]
	v_pk_fma_f32 v[154:155], v[6:7], v[120:121], v[166:167] op_sel_hi:[1,0,1]
	v_pk_fma_f32 v[126:127], v[6:7], v[140:141], v[126:127] op_sel_hi:[1,0,1]
	v_pk_fma_f32 v[146:147], v[6:7], v[148:149], v[146:147] op_sel_hi:[1,0,1]
	s_waitcnt lgkmcnt(1)
	v_pk_fma_f32 v[72:73], v[6:7], v[156:157], v[72:73] op_sel_hi:[1,0,1]
	v_add_u32_e32 v6, 0x200, v112
	v_mad_i64_i32 v[6:7], s[10:11], v6, s72, v[64:65]
	v_pk_fma_f32 v[76:77], v[8:9], v[86:87], v[84:85] op_sel_hi:[1,0,1]
	v_pk_fma_f32 v[84:85], v[8:9], v[90:91], v[162:163] op_sel_hi:[1,0,1]
	v_pk_fma_f32 v[92:93], v[8:9], v[96:97], v[92:93] op_sel_hi:[1,0,1]
	v_pk_fma_f32 v[98:99], v[8:9], v[102:103], v[98:99] op_sel_hi:[1,0,1]
	v_pk_fma_f32 v[104:105], v[8:9], v[110:111], v[104:105] op_sel_hi:[1,0,1]
	v_pk_fma_f32 v[152:153], v[8:9], v[120:121], v[164:165] op_sel_hi:[1,0,1]
	v_pk_fma_f32 v[124:125], v[8:9], v[140:141], v[124:125] op_sel_hi:[1,0,1]
	v_pk_fma_f32 v[144:145], v[8:9], v[148:149], v[144:145] op_sel_hi:[1,0,1]
	v_pk_fma_f32 v[74:75], v[8:9], v[156:157], v[74:75] op_sel_hi:[1,0,1]
	global_load_dwordx4 v[6:9], v[6:7], off
	v_mov_b32_e32 v86, v87
	s_waitcnt vmcnt(3)
	v_pk_fma_f32 v[76:77], v[82:83], v[86:87], v[76:77] op_sel_hi:[1,0,1]
	v_pk_fma_f32 v[78:79], v[80:81], v[86:87], v[78:79] op_sel_hi:[1,0,1]
	v_mov_b32_e32 v86, v91
	v_pk_fma_f32 v[84:85], v[82:83], v[86:87], v[84:85] op_sel_hi:[1,0,1]
	v_pk_fma_f32 v[86:87], v[80:81], v[86:87], v[88:89] op_sel_hi:[1,0,1]
	v_mov_b32_e32 v88, v97
	v_pk_fma_f32 v[90:91], v[82:83], v[88:89], v[92:93] op_sel_hi:[1,0,1]
	v_mov_b32_e32 v92, v103
	v_mov_b32_e32 v96, v111
	v_pk_fma_f32 v[88:89], v[80:81], v[88:89], v[94:95] op_sel_hi:[1,0,1]
	v_pk_fma_f32 v[94:95], v[82:83], v[92:93], v[98:99] op_sel_hi:[1,0,1]
	v_pk_fma_f32 v[98:99], v[82:83], v[96:97], v[104:105] op_sel_hi:[1,0,1]
	v_mov_b32_e32 v104, v141
	v_pk_fma_f32 v[92:93], v[80:81], v[92:93], v[100:101] op_sel_hi:[1,0,1]
	v_pk_fma_f32 v[96:97], v[80:81], v[96:97], v[108:109] op_sel_hi:[1,0,1]
	v_mov_b32_e32 v100, v121
	v_pk_fma_f32 v[108:109], v[82:83], v[104:105], v[124:125] op_sel_hi:[1,0,1]
	v_mov_b32_e32 v110, v149
	v_mov_b32_e32 v124, v157
	v_pk_fma_f32 v[102:103], v[82:83], v[100:101], v[152:153] op_sel_hi:[1,0,1]
	v_pk_fma_f32 v[100:101], v[80:81], v[100:101], v[154:155] op_sel_hi:[1,0,1]
	v_pk_fma_f32 v[104:105], v[80:81], v[104:105], v[126:127] op_sel_hi:[1,0,1]
	v_pk_fma_f32 v[120:121], v[82:83], v[110:111], v[144:145] op_sel_hi:[1,0,1]
	v_pk_fma_f32 v[110:111], v[80:81], v[110:111], v[146:147] op_sel_hi:[1,0,1]
	v_pk_fma_f32 v[72:73], v[80:81], v[124:125], v[72:73] op_sel_hi:[1,0,1]
	v_add_u32_e32 v80, 0x240, v112
	v_pk_fma_f32 v[74:75], v[82:83], v[124:125], v[74:75] op_sel_hi:[1,0,1]
	v_mad_i64_i32 v[80:81], s[10:11], v80, s72, v[64:65]
	s_waitcnt vmcnt(2)
	v_pk_fma_f32 v[76:77], v[4:5], v[66:67], v[76:77] op_sel_hi:[1,0,1]
	v_pk_fma_f32 v[78:79], v[2:3], v[66:67], v[78:79] op_sel_hi:[1,0,1]
	v_mov_b32_e32 v66, v67
	v_pk_fma_f32 v[82:83], v[4:5], v[68:69], v[84:85] op_sel_hi:[1,0,1]
	v_pk_fma_f32 v[84:85], v[2:3], v[68:69], v[86:87] op_sel_hi:[1,0,1]
	v_pk_fma_f32 v[86:87], v[4:5], v[70:71], v[90:91] op_sel_hi:[1,0,1]
	v_pk_fma_f32 v[88:89], v[2:3], v[70:71], v[88:89] op_sel_hi:[1,0,1]
	v_pk_fma_f32 v[90:91], v[4:5], v[106:107], v[94:95] op_sel_hi:[1,0,1]
	v_pk_fma_f32 v[92:93], v[2:3], v[106:107], v[92:93] op_sel_hi:[1,0,1]
	v_pk_fma_f32 v[124:125], v[4:5], v[118:119], v[98:99] op_sel_hi:[1,0,1]
	v_pk_fma_f32 v[96:97], v[2:3], v[118:119], v[96:97] op_sel_hi:[1,0,1]
	v_pk_fma_f32 v[126:127], v[4:5], v[122:123], v[102:103] op_sel_hi:[1,0,1]
	v_pk_fma_f32 v[140:141], v[2:3], v[122:123], v[100:101] op_sel_hi:[1,0,1]
	v_pk_fma_f32 v[144:145], v[4:5], v[142:143], v[108:109] op_sel_hi:[1,0,1]
	v_pk_fma_f32 v[146:147], v[2:3], v[142:143], v[104:105] op_sel_hi:[1,0,1]
	v_pk_fma_f32 v[120:121], v[4:5], v[150:151], v[120:121] op_sel_hi:[1,0,1]
	v_pk_fma_f32 v[148:149], v[2:3], v[150:151], v[110:111] op_sel_hi:[1,0,1]
	s_waitcnt lgkmcnt(0)
	v_pk_fma_f32 v[152:153], v[4:5], v[158:159], v[74:75] op_sel_hi:[1,0,1]
	v_pk_fma_f32 v[154:155], v[2:3], v[158:159], v[72:73] op_sel_hi:[1,0,1]
	global_load_dwordx4 v[2:5], v[80:81], off
	s_waitcnt vmcnt(2)
	v_pk_fma_f32 v[104:105], v[116:117], v[66:67], v[76:77] op_sel_hi:[1,0,1]
	v_pk_fma_f32 v[102:103], v[114:115], v[66:67], v[78:79] op_sel_hi:[1,0,1]
	v_mov_b32_e32 v66, v69
	v_pk_fma_f32 v[110:111], v[116:117], v[66:67], v[82:83] op_sel_hi:[1,0,1]
	v_pk_fma_f32 v[108:109], v[114:115], v[66:67], v[84:85] op_sel_hi:[1,0,1]
	v_mov_b32_e32 v66, v71
	v_pk_fma_f32 v[100:101], v[116:117], v[66:67], v[86:87] op_sel_hi:[1,0,1]
	v_pk_fma_f32 v[98:99], v[114:115], v[66:67], v[88:89] op_sel_hi:[1,0,1]
	v_mov_b32_e32 v66, v107
	v_pk_fma_f32 v[94:95], v[116:117], v[66:67], v[90:91] op_sel_hi:[1,0,1]
	v_pk_fma_f32 v[92:93], v[114:115], v[66:67], v[92:93] op_sel_hi:[1,0,1]
	v_mov_b32_e32 v66, v119
	v_pk_fma_f32 v[88:89], v[116:117], v[66:67], v[124:125] op_sel_hi:[1,0,1]
	v_pk_fma_f32 v[90:91], v[114:115], v[66:67], v[96:97] op_sel_hi:[1,0,1]
	v_mov_b32_e32 v66, v123
	ds_read2st64_b32 v[72:73], v12 offset0:8 offset1:9
	v_pk_fma_f32 v[86:87], v[116:117], v[66:67], v[126:127] op_sel_hi:[1,0,1]
	v_pk_fma_f32 v[84:85], v[114:115], v[66:67], v[140:141] op_sel_hi:[1,0,1]
	v_mov_b32_e32 v66, v143
	v_pk_fma_f32 v[82:83], v[116:117], v[66:67], v[144:145] op_sel_hi:[1,0,1]
	v_pk_fma_f32 v[80:81], v[114:115], v[66:67], v[146:147] op_sel_hi:[1,0,1]
	v_mov_b32_e32 v66, v151
	v_pk_fma_f32 v[78:79], v[116:117], v[66:67], v[120:121] op_sel_hi:[1,0,1]
	v_pk_fma_f32 v[74:75], v[114:115], v[66:67], v[148:149] op_sel_hi:[1,0,1]
	v_mov_b32_e32 v66, v159
	v_pk_fma_f32 v[70:71], v[116:117], v[66:67], v[152:153] op_sel_hi:[1,0,1]
	v_pk_fma_f32 v[76:77], v[114:115], v[66:67], v[154:155] op_sel_hi:[1,0,1]
	ds_read2st64_b32 v[66:67], v12 offset0:10 offset1:11
	ds_read2st64_b32 v[68:69], v12 offset0:12 offset1:13
	ds_read2st64_b32 v[96:97], v12 offset0:14 offset1:15
	ds_read2st64_b32 v[124:125], v12 offset0:24 offset1:25
	s_waitcnt vmcnt(1) lgkmcnt(4)
	v_pk_fma_f32 v[122:123], v[8:9], v[72:73], v[104:105] op_sel_hi:[1,0,1]
	v_pk_fma_f32 v[126:127], v[6:7], v[72:73], v[102:103] op_sel_hi:[1,0,1]
	ds_read2st64_b32 v[106:107], v12 offset0:26 offset1:27
	ds_read2st64_b32 v[104:105], v12 offset0:28 offset1:29
	ds_read2st64_b32 v[102:103], v12 offset0:30 offset1:31
	ds_read2st64_b32 v[140:141], v12 offset0:40 offset1:41
	v_add_u32_e32 v72, 0x280, v112
	s_waitcnt lgkmcnt(4)
	v_pk_fma_f32 v[142:143], v[6:7], v[124:125], v[108:109] op_sel_hi:[1,0,1]
	v_mad_i64_i32 v[108:109], s[10:11], v72, s72, v[64:65]
	global_load_dwordx4 v[114:117], v[108:109], off
	ds_read2st64_b32 v[144:145], v12 offset0:42 offset1:43
	ds_read2st64_b32 v[146:147], v12 offset0:44 offset1:45
	ds_read2st64_b32 v[108:109], v12 offset0:46 offset1:47
	ds_read2st64_b32 v[148:149], v12 offset0:56 offset1:57
	s_waitcnt lgkmcnt(4)
	v_pk_fma_f32 v[150:151], v[6:7], v[140:141], v[98:99] op_sel_hi:[1,0,1]
	ds_read2st64_b32 v[152:153], v12 offset0:58 offset1:59
	ds_read2st64_b32 v[154:155], v12 offset0:60 offset1:61
	ds_read2st64_b32 v[98:99], v12 offset0:62 offset1:63
	ds_read2st64_b32 v[156:157], v12 offset0:72 offset1:73
	v_add_u32_e32 v72, 0x2c0, v112
	s_waitcnt lgkmcnt(4)
	v_pk_fma_f32 v[158:159], v[6:7], v[148:149], v[92:93] op_sel_hi:[1,0,1]
	ds_read2st64_b32 v[162:163], v12 offset0:74 offset1:75
	ds_read2st64_b32 v[164:165], v12 offset0:76 offset1:77
	ds_read2st64_b32 v[92:93], v12 offset0:78 offset1:79
	ds_read2st64_b32 v[168:169], v12 offset0:88 offset1:89
	s_waitcnt lgkmcnt(4)
	v_pk_fma_f32 v[166:167], v[8:9], v[156:157], v[88:89] op_sel_hi:[1,0,1]
	v_mad_i64_i32 v[88:89], s[10:11], v72, s72, v[64:65]
	global_load_dwordx4 v[118:121], v[88:89], off
	ds_read2st64_b32 v[170:171], v12 offset0:90 offset1:91
	ds_read2st64_b32 v[172:173], v12 offset0:92 offset1:93
	ds_read2st64_b32 v[88:89], v12 offset0:94 offset1:95
	ds_read2st64_b32 v[174:175], v12 offset0:104 offset1:105
	s_waitcnt lgkmcnt(4)
	v_pk_fma_f32 v[176:177], v[6:7], v[168:169], v[84:85] op_sel_hi:[1,0,1]
	ds_read2st64_b32 v[178:179], v12 offset0:106 offset1:107
	ds_read2st64_b32 v[180:181], v12 offset0:108 offset1:109
	ds_read2st64_b32 v[84:85], v12 offset0:110 offset1:111
	ds_read2st64_b32 v[182:183], v12 offset0:120 offset1:121
	v_pk_fma_f32 v[110:111], v[8:9], v[124:125], v[110:111] op_sel_hi:[1,0,1]
	s_waitcnt lgkmcnt(4)
	v_pk_fma_f32 v[184:185], v[6:7], v[174:175], v[80:81] op_sel_hi:[1,0,1]
	ds_read2st64_b32 v[186:187], v12 offset0:122 offset1:123
	ds_read2st64_b32 v[188:189], v12 offset0:124 offset1:125
	ds_read2st64_b32 v[80:81], v12 offset0:126 offset1:127
	ds_read2st64_b32 v[192:193], v12 offset0:136 offset1:137
	v_pk_fma_f32 v[90:91], v[6:7], v[156:157], v[90:91] op_sel_hi:[1,0,1]
	s_waitcnt lgkmcnt(4)
	v_pk_fma_f32 v[190:191], v[8:9], v[182:183], v[78:79] op_sel_hi:[1,0,1]
	v_pk_fma_f32 v[74:75], v[6:7], v[182:183], v[74:75] op_sel_hi:[1,0,1]
	ds_read2st64_b32 v[194:195], v12 offset0:138 offset1:139
	ds_read2st64_b32 v[196:197], v12 offset0:140 offset1:141
	ds_read2st64_b32 v[78:79], v12 offset0:142 offset1:143
	s_waitcnt lgkmcnt(3)
	v_pk_fma_f32 v[76:77], v[6:7], v[192:193], v[76:77] op_sel_hi:[1,0,1]
	v_mov_b32_e32 v6, v73
	v_mov_b32_e32 v12, v125
	v_pk_fma_f32 v[100:101], v[8:9], v[140:141], v[100:101] op_sel_hi:[1,0,1]
	v_pk_fma_f32 v[94:95], v[8:9], v[148:149], v[94:95] op_sel_hi:[1,0,1]
	v_pk_fma_f32 v[198:199], v[8:9], v[192:193], v[70:71] op_sel_hi:[1,0,1]
	v_add_u32_e32 v70, 0x340, v112
	v_pk_fma_f32 v[86:87], v[8:9], v[168:169], v[86:87] op_sel_hi:[1,0,1]
	v_pk_fma_f32 v[82:83], v[8:9], v[174:175], v[82:83] op_sel_hi:[1,0,1]
	v_mad_i64_i32 v[70:71], s[10:11], v70, s72, v[64:65]
	global_load_dwordx4 v[70:73], v[70:71], off
	s_waitcnt vmcnt(3)
	v_pk_fma_f32 v[122:123], v[4:5], v[6:7], v[122:123] op_sel_hi:[1,0,1]
	v_pk_fma_f32 v[126:127], v[2:3], v[6:7], v[126:127] op_sel_hi:[1,0,1]
	v_pk_fma_f32 v[110:111], v[4:5], v[12:13], v[110:111] op_sel_hi:[1,0,1]
	v_add_u32_e32 v6, 0x300, v112
	v_pk_fma_f32 v[124:125], v[2:3], v[12:13], v[142:143] op_sel_hi:[1,0,1]
	v_mov_b32_e32 v12, v141
	v_mad_i64_i32 v[6:7], s[10:11], v6, s72, v[64:65]
	v_pk_fma_f32 v[100:101], v[4:5], v[12:13], v[100:101] op_sel_hi:[1,0,1]
	v_pk_fma_f32 v[140:141], v[2:3], v[12:13], v[150:151] op_sel_hi:[1,0,1]
	v_mov_b32_e32 v12, v149
	global_load_dwordx4 v[6:9], v[6:7], off
	v_pk_fma_f32 v[94:95], v[4:5], v[12:13], v[94:95] op_sel_hi:[1,0,1]
	v_pk_fma_f32 v[142:143], v[2:3], v[12:13], v[158:159] op_sel_hi:[1,0,1]
	v_mov_b32_e32 v12, v157
	v_pk_fma_f32 v[148:149], v[4:5], v[12:13], v[166:167] op_sel_hi:[1,0,1]
	v_pk_fma_f32 v[90:91], v[2:3], v[12:13], v[90:91] op_sel_hi:[1,0,1]
	v_mov_b32_e32 v12, v169
	v_pk_fma_f32 v[86:87], v[4:5], v[12:13], v[86:87] op_sel_hi:[1,0,1]
	v_pk_fma_f32 v[150:151], v[2:3], v[12:13], v[176:177] op_sel_hi:[1,0,1]
	v_mov_b32_e32 v12, v175
	v_pk_fma_f32 v[82:83], v[4:5], v[12:13], v[82:83] op_sel_hi:[1,0,1]
	v_pk_fma_f32 v[156:157], v[2:3], v[12:13], v[184:185] op_sel_hi:[1,0,1]
	v_mov_b32_e32 v12, v183
	v_pk_fma_f32 v[158:159], v[4:5], v[12:13], v[190:191] op_sel_hi:[1,0,1]
	v_pk_fma_f32 v[74:75], v[2:3], v[12:13], v[74:75] op_sel_hi:[1,0,1]
	v_mov_b32_e32 v12, v193
	v_pk_fma_f32 v[166:167], v[4:5], v[12:13], v[198:199] op_sel_hi:[1,0,1]
	v_pk_fma_f32 v[76:77], v[2:3], v[12:13], v[76:77] op_sel_hi:[1,0,1]
	v_mov_b32_e32 v12, v67
	v_add_u32_e32 v2, 0x380, v112
	v_mad_i64_i32 v[2:3], s[10:11], v2, s72, v[64:65]
	global_load_dwordx4 v[2:5], v[2:3], off
	s_waitcnt vmcnt(4)
	v_pk_fma_f32 v[122:123], v[116:117], v[66:67], v[122:123] op_sel_hi:[1,0,1]
	v_pk_fma_f32 v[126:127], v[114:115], v[66:67], v[126:127] op_sel_hi:[1,0,1]
	v_pk_fma_f32 v[110:111], v[116:117], v[106:107], v[110:111] op_sel_hi:[1,0,1]
	v_pk_fma_f32 v[124:125], v[114:115], v[106:107], v[124:125] op_sel_hi:[1,0,1]
	v_pk_fma_f32 v[140:141], v[114:115], v[144:145], v[140:141] op_sel_hi:[1,0,1]
	v_pk_fma_f32 v[142:143], v[114:115], v[152:153], v[142:143] op_sel_hi:[1,0,1]
	v_pk_fma_f32 v[90:91], v[114:115], v[162:163], v[90:91] op_sel_hi:[1,0,1]
	v_pk_fma_f32 v[150:151], v[114:115], v[170:171], v[150:151] op_sel_hi:[1,0,1]
	v_pk_fma_f32 v[156:157], v[114:115], v[178:179], v[156:157] op_sel_hi:[1,0,1]
	v_pk_fma_f32 v[74:75], v[114:115], v[186:187], v[74:75] op_sel_hi:[1,0,1]
	s_waitcnt lgkmcnt(2)
	v_pk_fma_f32 v[76:77], v[114:115], v[194:195], v[76:77] op_sel_hi:[1,0,1]
	v_pk_fma_f32 v[100:101], v[116:117], v[144:145], v[100:101] op_sel_hi:[1,0,1]
	v_pk_fma_f32 v[94:95], v[116:117], v[152:153], v[94:95] op_sel_hi:[1,0,1]
	s_waitcnt vmcnt(3)
	v_pk_fma_f32 v[114:115], v[120:121], v[12:13], v[122:123] op_sel_hi:[1,0,1]
	v_pk_fma_f32 v[122:123], v[118:119], v[12:13], v[126:127] op_sel_hi:[1,0,1]
	v_mov_b32_e32 v12, v107
	v_pk_fma_f32 v[106:107], v[120:121], v[12:13], v[110:111] op_sel_hi:[1,0,1]
	v_pk_fma_f32 v[110:111], v[118:119], v[12:13], v[124:125] op_sel_hi:[1,0,1]
	v_mov_b32_e32 v12, v145
	v_pk_fma_f32 v[100:101], v[120:121], v[12:13], v[100:101] op_sel_hi:[1,0,1]
	v_pk_fma_f32 v[124:125], v[118:119], v[12:13], v[140:141] op_sel_hi:[1,0,1]
	v_mov_b32_e32 v12, v153
	v_pk_fma_f32 v[94:95], v[120:121], v[12:13], v[94:95] op_sel_hi:[1,0,1]
	v_pk_fma_f32 v[126:127], v[118:119], v[12:13], v[142:143] op_sel_hi:[1,0,1]
	v_add_u32_e32 v12, 0x3c0, v112
	v_mad_i64_i32 v[64:65], s[10:11], v12, s72, v[64:65]
	global_load_dwordx4 v[64:67], v[64:65], off
	v_pk_fma_f32 v[148:149], v[116:117], v[162:163], v[148:149] op_sel_hi:[1,0,1]
	v_mov_b32_e32 v12, v163
	v_pk_fma_f32 v[86:87], v[116:117], v[170:171], v[86:87] op_sel_hi:[1,0,1]
	v_pk_fma_f32 v[112:113], v[120:121], v[12:13], v[148:149] op_sel_hi:[1,0,1]
	v_pk_fma_f32 v[90:91], v[118:119], v[12:13], v[90:91] op_sel_hi:[1,0,1]
	v_mov_b32_e32 v12, v171
	v_pk_fma_f32 v[82:83], v[116:117], v[178:179], v[82:83] op_sel_hi:[1,0,1]
	v_pk_fma_f32 v[86:87], v[120:121], v[12:13], v[86:87] op_sel_hi:[1,0,1]
	v_pk_fma_f32 v[140:141], v[118:119], v[12:13], v[150:151] op_sel_hi:[1,0,1]
	v_mov_b32_e32 v12, v179
	v_pk_fma_f32 v[158:159], v[116:117], v[186:187], v[158:159] op_sel_hi:[1,0,1]
	v_pk_fma_f32 v[82:83], v[120:121], v[12:13], v[82:83] op_sel_hi:[1,0,1]
	v_pk_fma_f32 v[142:143], v[118:119], v[12:13], v[156:157] op_sel_hi:[1,0,1]
	v_mov_b32_e32 v12, v187
	v_pk_fma_f32 v[116:117], v[116:117], v[194:195], v[166:167] op_sel_hi:[1,0,1]
	v_pk_fma_f32 v[144:145], v[120:121], v[12:13], v[158:159] op_sel_hi:[1,0,1]
	v_pk_fma_f32 v[74:75], v[118:119], v[12:13], v[74:75] op_sel_hi:[1,0,1]
	v_mov_b32_e32 v12, v195
	v_pk_fma_f32 v[116:117], v[120:121], v[12:13], v[116:117] op_sel_hi:[1,0,1]
	v_pk_fma_f32 v[76:77], v[118:119], v[12:13], v[76:77] op_sel_hi:[1,0,1]
	v_mov_b32_e32 v12, v69
	s_waitcnt vmcnt(2)
	v_pk_fma_f32 v[114:115], v[8:9], v[68:69], v[114:115] op_sel_hi:[1,0,1]
	v_pk_fma_f32 v[118:119], v[6:7], v[68:69], v[122:123] op_sel_hi:[1,0,1]
	v_pk_fma_f32 v[106:107], v[8:9], v[104:105], v[106:107] op_sel_hi:[1,0,1]
	v_pk_fma_f32 v[110:111], v[6:7], v[104:105], v[110:111] op_sel_hi:[1,0,1]
	v_pk_fma_f32 v[120:121], v[6:7], v[146:147], v[124:125] op_sel_hi:[1,0,1]
	v_pk_fma_f32 v[122:123], v[6:7], v[154:155], v[126:127] op_sel_hi:[1,0,1]
	v_pk_fma_f32 v[90:91], v[6:7], v[164:165], v[90:91] op_sel_hi:[1,0,1]
	v_pk_fma_f32 v[124:125], v[6:7], v[172:173], v[140:141] op_sel_hi:[1,0,1]
	v_pk_fma_f32 v[126:127], v[6:7], v[180:181], v[142:143] op_sel_hi:[1,0,1]
	v_pk_fma_f32 v[74:75], v[6:7], v[188:189], v[74:75] op_sel_hi:[1,0,1]
	s_waitcnt lgkmcnt(1)
	v_pk_fma_f32 v[6:7], v[6:7], v[196:197], v[76:77] op_sel_hi:[1,0,1]
	v_pk_fma_f32 v[68:69], v[72:73], v[12:13], v[114:115] op_sel_hi:[1,0,1]
	v_pk_fma_f32 v[76:77], v[70:71], v[12:13], v[118:119] op_sel_hi:[1,0,1]
	v_mov_b32_e32 v12, v105
	v_pk_fma_f32 v[100:101], v[8:9], v[146:147], v[100:101] op_sel_hi:[1,0,1]
	v_pk_fma_f32 v[104:105], v[72:73], v[12:13], v[106:107] op_sel_hi:[1,0,1]
	v_pk_fma_f32 v[106:107], v[70:71], v[12:13], v[110:111] op_sel_hi:[1,0,1]
	v_mov_b32_e32 v12, v147
	v_pk_fma_f32 v[94:95], v[8:9], v[154:155], v[94:95] op_sel_hi:[1,0,1]
	v_pk_fma_f32 v[100:101], v[72:73], v[12:13], v[100:101] op_sel_hi:[1,0,1]
	v_pk_fma_f32 v[110:111], v[70:71], v[12:13], v[120:121] op_sel_hi:[1,0,1]
	v_mov_b32_e32 v12, v155
	v_pk_fma_f32 v[112:113], v[8:9], v[164:165], v[112:113] op_sel_hi:[1,0,1]
	v_pk_fma_f32 v[94:95], v[72:73], v[12:13], v[94:95] op_sel_hi:[1,0,1]
	v_pk_fma_f32 v[114:115], v[70:71], v[12:13], v[122:123] op_sel_hi:[1,0,1]
	v_mov_b32_e32 v12, v165
	v_pk_fma_f32 v[86:87], v[8:9], v[172:173], v[86:87] op_sel_hi:[1,0,1]
	v_pk_fma_f32 v[112:113], v[72:73], v[12:13], v[112:113] op_sel_hi:[1,0,1]
	v_pk_fma_f32 v[90:91], v[70:71], v[12:13], v[90:91] op_sel_hi:[1,0,1]
	v_mov_b32_e32 v12, v173
	v_pk_fma_f32 v[82:83], v[8:9], v[180:181], v[82:83] op_sel_hi:[1,0,1]
	v_pk_fma_f32 v[140:141], v[8:9], v[188:189], v[144:145] op_sel_hi:[1,0,1]
	v_pk_fma_f32 v[8:9], v[8:9], v[196:197], v[116:117] op_sel_hi:[1,0,1]
	v_pk_fma_f32 v[86:87], v[72:73], v[12:13], v[86:87] op_sel_hi:[1,0,1]
	v_pk_fma_f32 v[116:117], v[70:71], v[12:13], v[124:125] op_sel_hi:[1,0,1]
	v_mov_b32_e32 v12, v181
	v_pk_fma_f32 v[82:83], v[72:73], v[12:13], v[82:83] op_sel_hi:[1,0,1]
	v_pk_fma_f32 v[118:119], v[70:71], v[12:13], v[126:127] op_sel_hi:[1,0,1]
	v_mov_b32_e32 v12, v189
	v_pk_fma_f32 v[120:121], v[72:73], v[12:13], v[140:141] op_sel_hi:[1,0,1]
	v_pk_fma_f32 v[74:75], v[70:71], v[12:13], v[74:75] op_sel_hi:[1,0,1]
	v_mov_b32_e32 v12, v197
	v_pk_fma_f32 v[6:7], v[70:71], v[12:13], v[6:7] op_sel_hi:[1,0,1]
	v_pk_fma_f32 v[8:9], v[72:73], v[12:13], v[8:9] op_sel_hi:[1,0,1]
	s_waitcnt vmcnt(1)
	v_pk_fma_f32 v[68:69], v[4:5], v[96:97], v[68:69] op_sel_hi:[1,0,1]
	v_pk_fma_f32 v[70:71], v[2:3], v[96:97], v[76:77] op_sel_hi:[1,0,1]
	v_pk_fma_f32 v[72:73], v[4:5], v[102:103], v[104:105] op_sel_hi:[1,0,1]
	v_pk_fma_f32 v[76:77], v[2:3], v[102:103], v[106:107] op_sel_hi:[1,0,1]
	v_pk_fma_f32 v[104:105], v[2:3], v[108:109], v[110:111] op_sel_hi:[1,0,1]
	v_pk_fma_f32 v[106:107], v[2:3], v[98:99], v[114:115] op_sel_hi:[1,0,1]
	v_pk_fma_f32 v[110:111], v[4:5], v[92:93], v[112:113] op_sel_hi:[1,0,1]
	v_pk_fma_f32 v[90:91], v[2:3], v[92:93], v[90:91] op_sel_hi:[1,0,1]
	v_pk_fma_f32 v[112:113], v[2:3], v[88:89], v[116:117] op_sel_hi:[1,0,1]
	v_pk_fma_f32 v[114:115], v[2:3], v[84:85], v[118:119] op_sel_hi:[1,0,1]
	v_pk_fma_f32 v[118:119], v[2:3], v[80:81], v[74:75] op_sel_hi:[1,0,1]
	s_waitcnt lgkmcnt(0)
	v_pk_fma_f32 v[2:3], v[2:3], v[78:79], v[6:7] op_sel_hi:[1,0,1]
	v_mov_b32_e32 v6, v97
	v_mov_b32_e32 v12, v103
	v_pk_fma_f32 v[100:101], v[4:5], v[108:109], v[100:101] op_sel_hi:[1,0,1]
	v_pk_fma_f32 v[94:95], v[4:5], v[98:99], v[94:95] op_sel_hi:[1,0,1]
	v_pk_fma_f32 v[86:87], v[4:5], v[88:89], v[86:87] op_sel_hi:[1,0,1]
	v_pk_fma_f32 v[82:83], v[4:5], v[84:85], v[82:83] op_sel_hi:[1,0,1]
	v_pk_fma_f32 v[116:117], v[4:5], v[80:81], v[120:121] op_sel_hi:[1,0,1]
	v_pk_fma_f32 v[4:5], v[4:5], v[78:79], v[8:9] op_sel_hi:[1,0,1]
	s_waitcnt vmcnt(0)
	v_pk_fma_f32 v[8:9], v[66:67], v[6:7], v[68:69] op_sel_hi:[1,0,1]
	v_pk_fma_f32 v[6:7], v[64:65], v[6:7], v[70:71] op_sel_hi:[1,0,1]
	v_pk_fma_f32 v[70:71], v[66:67], v[12:13], v[72:73] op_sel_hi:[1,0,1]
	v_pk_fma_f32 v[72:73], v[64:65], v[12:13], v[76:77] op_sel_hi:[1,0,1]
	v_mov_b32_e32 v12, v109
	v_pk_fma_f32 v[96:97], v[66:67], v[12:13], v[100:101] op_sel_hi:[1,0,1]
	v_pk_fma_f32 v[100:101], v[64:65], v[12:13], v[104:105] op_sel_hi:[1,0,1]
	v_mov_b32_e32 v12, v99
	v_pk_fma_f32 v[94:95], v[66:67], v[12:13], v[94:95] op_sel_hi:[1,0,1]
	v_pk_fma_f32 v[98:99], v[64:65], v[12:13], v[106:107] op_sel_hi:[1,0,1]
	v_mov_b32_e32 v12, v93
	v_pk_fma_f32 v[102:103], v[66:67], v[12:13], v[110:111] op_sel_hi:[1,0,1]
	v_pk_fma_f32 v[104:105], v[64:65], v[12:13], v[90:91] op_sel_hi:[1,0,1]
	v_mov_b32_e32 v12, v89
	v_pk_fma_f32 v[108:109], v[66:67], v[12:13], v[86:87] op_sel_hi:[1,0,1]
	v_pk_fma_f32 v[106:107], v[64:65], v[12:13], v[112:113] op_sel_hi:[1,0,1]
	v_mov_b32_e32 v12, v85
	v_pk_fma_f32 v[120:121], v[66:67], v[12:13], v[82:83] op_sel_hi:[1,0,1]
	v_pk_fma_f32 v[110:111], v[64:65], v[12:13], v[114:115] op_sel_hi:[1,0,1]
	v_mov_b32_e32 v12, v81
	v_pk_fma_f32 v[74:75], v[66:67], v[12:13], v[116:117] op_sel_hi:[1,0,1]
	v_pk_fma_f32 v[80:81], v[64:65], v[12:13], v[118:119] op_sel_hi:[1,0,1]
	v_mov_b32_e32 v12, v79
	v_pk_fma_f32 v[68:69], v[64:65], v[12:13], v[2:3] op_sel_hi:[1,0,1]
	v_and_b32_e32 v3, 64, v137
	v_pk_fma_f32 v[66:67], v[66:67], v[12:13], v[4:5] op_sel_hi:[1,0,1]
	v_xor_b32_e32 v2, 8, v137
	v_add_u32_e32 v12, 64, v3
	v_cmp_lt_i32_e32 vcc, v2, v12
	v_xor_b32_e32 v4, 16, v137
	s_nop 0
	v_cndmask_b32_e32 v2, v137, v2, vcc
	v_lshlrev_b32_e32 v140, 2, v2
	ds_bpermute_b32 v78, v140, v100
	ds_bpermute_b32 v79, v140, v101
	ds_bpermute_b32 v82, v140, v96
	ds_bpermute_b32 v83, v140, v97
	ds_bpermute_b32 v112, v140, v108
	ds_bpermute_b32 v113, v140, v109
	ds_bpermute_b32 v114, v140, v110
	ds_bpermute_b32 v115, v140, v111
	v_cmp_lt_i32_e32 vcc, v4, v12
	s_waitcnt lgkmcnt(6)
	v_pk_add_f32 v[78:79], v[100:101], v[78:79]
	s_waitcnt lgkmcnt(4)
	v_pk_add_f32 v[86:87], v[96:97], v[82:83]
	v_cndmask_b32_e32 v4, v137, v4, vcc
	v_lshlrev_b32_e32 v141, 2, v4
	s_waitcnt lgkmcnt(2)
	v_pk_add_f32 v[108:109], v[108:109], v[112:113]
	s_waitcnt lgkmcnt(0)
	v_pk_add_f32 v[114:115], v[110:111], v[114:115]
	ds_bpermute_b32 v84, v141, v78
	ds_bpermute_b32 v85, v141, v79
	ds_bpermute_b32 v88, v141, v86
	ds_bpermute_b32 v89, v141, v87
	ds_bpermute_b32 v112, v141, v108
	ds_bpermute_b32 v113, v141, v109
	ds_bpermute_b32 v116, v141, v114
	ds_bpermute_b32 v117, v141, v115
	ds_bpermute_b32 v118, v140, v120
	ds_bpermute_b32 v119, v140, v121
	s_waitcnt lgkmcnt(8)
	v_pk_add_f32 v[78:79], v[78:79], v[84:85]
	s_waitcnt lgkmcnt(6)
	v_pk_add_f32 v[84:85], v[86:87], v[88:89]
	ds_bpermute_b32 v88, v140, v98
	ds_bpermute_b32 v89, v140, v99
	ds_bpermute_b32 v90, v140, v94
	ds_bpermute_b32 v91, v140, v95
	s_waitcnt lgkmcnt(8)
	v_pk_add_f32 v[108:109], v[108:109], v[112:113]
	s_waitcnt lgkmcnt(6)
	v_pk_add_f32 v[112:113], v[114:115], v[116:117]
	s_waitcnt lgkmcnt(4)
	v_pk_add_f32 v[116:117], v[120:121], v[118:119]
	ds_bpermute_b32 v120, v140, v80
	ds_bpermute_b32 v121, v140, v81
	ds_bpermute_b32 v122, v140, v74
	ds_bpermute_b32 v123, v140, v75
	ds_bpermute_b32 v2, v140, v6
	ds_bpermute_b32 v3, v140, v7
	ds_bpermute_b32 v64, v140, v72
	ds_bpermute_b32 v65, v140, v73
	s_waitcnt lgkmcnt(10)
	v_pk_add_f32 v[88:89], v[98:99], v[88:89]
	s_waitcnt lgkmcnt(8)
	v_pk_add_f32 v[94:95], v[94:95], v[90:91]
	s_waitcnt lgkmcnt(6)
	v_pk_add_f32 v[80:81], v[80:81], v[120:121]
	s_waitcnt lgkmcnt(4)
	v_pk_add_f32 v[122:123], v[74:75], v[122:123]
	ds_bpermute_b32 v92, v141, v88
	ds_bpermute_b32 v93, v141, v89
	ds_bpermute_b32 v96, v141, v94
	ds_bpermute_b32 v97, v141, v95
	ds_bpermute_b32 v98, v140, v104
	ds_bpermute_b32 v99, v140, v105
	ds_bpermute_b32 v120, v141, v80
	ds_bpermute_b32 v121, v141, v81
	ds_bpermute_b32 v124, v141, v122
	ds_bpermute_b32 v125, v141, v123
	s_waitcnt lgkmcnt(12)
	v_pk_add_f32 v[2:3], v[6:7], v[2:3]
	v_xor_b32_e32 v6, 32, v137
	v_cmp_lt_i32_e32 vcc, v6, v12
	s_waitcnt lgkmcnt(10)
	v_pk_add_f32 v[64:65], v[72:73], v[64:65]
	ds_bpermute_b32 v7, v140, v9
	v_cndmask_b32_e32 v6, v137, v6, vcc
	v_lshlrev_b32_e32 v12, 2, v6
	ds_bpermute_b32 v6, v140, v8
	ds_bpermute_b32 v72, v141, v64
	ds_bpermute_b32 v73, v141, v65
	ds_bpermute_b32 v76, v140, v70
	ds_bpermute_b32 v77, v140, v71
	s_waitcnt lgkmcnt(14)
	v_pk_add_f32 v[88:89], v[88:89], v[92:93]
	s_waitcnt lgkmcnt(12)
	v_pk_add_f32 v[92:93], v[94:95], v[96:97]
	s_waitcnt lgkmcnt(10)
	v_pk_add_f32 v[96:97], v[104:105], v[98:99]
	ds_bpermute_b32 v100, v140, v102
	ds_bpermute_b32 v101, v140, v103
	ds_bpermute_b32 v104, v140, v106
	ds_bpermute_b32 v105, v140, v107
	s_waitcnt lgkmcnt(12)
	v_pk_add_f32 v[74:75], v[80:81], v[120:121]
	ds_bpermute_b32 v126, v140, v68
	ds_bpermute_b32 v127, v140, v69
	s_waitcnt lgkmcnt(12)
	v_pk_add_f32 v[80:81], v[122:123], v[124:125]
	ds_bpermute_b32 v122, v140, v66
	ds_bpermute_b32 v123, v140, v67
	s_waitcnt lgkmcnt(12)
	v_pk_add_f32 v[6:7], v[8:9], v[6:7]
	s_waitcnt lgkmcnt(10)
	v_pk_add_f32 v[64:65], v[64:65], v[72:73]
	s_waitcnt lgkmcnt(8)
	v_pk_add_f32 v[72:73], v[70:71], v[76:77]
	s_waitcnt lgkmcnt(6)
	v_pk_add_f32 v[100:101], v[102:103], v[100:101]
	s_waitcnt lgkmcnt(4)
	v_pk_add_f32 v[104:105], v[106:107], v[104:105]
	s_waitcnt lgkmcnt(2)
	v_pk_add_f32 v[68:69], v[68:69], v[126:127]
	s_waitcnt lgkmcnt(0)
	v_pk_add_f32 v[122:123], v[66:67], v[122:123]
	ds_bpermute_b32 v4, v141, v2
	ds_bpermute_b32 v5, v141, v3
	ds_bpermute_b32 v8, v141, v6
	ds_bpermute_b32 v9, v141, v7
	ds_bpermute_b32 v76, v141, v72
	ds_bpermute_b32 v77, v141, v73
	ds_bpermute_b32 v98, v141, v96
	ds_bpermute_b32 v99, v141, v97
	ds_bpermute_b32 v102, v141, v100
	ds_bpermute_b32 v103, v141, v101
	ds_bpermute_b32 v106, v141, v104
	ds_bpermute_b32 v107, v141, v105
	ds_bpermute_b32 v118, v141, v116
	ds_bpermute_b32 v119, v141, v117
	ds_bpermute_b32 v124, v141, v68
	ds_bpermute_b32 v125, v141, v69
	ds_bpermute_b32 v126, v141, v122
	ds_bpermute_b32 v127, v141, v123
	s_waitcnt lgkmcnt(14)
	v_pk_add_f32 v[2:3], v[2:3], v[4:5]
	v_pk_add_f32 v[6:7], v[6:7], v[8:9]
	s_waitcnt lgkmcnt(12)
	v_pk_add_f32 v[72:73], v[72:73], v[76:77]
	s_waitcnt lgkmcnt(10)
	v_pk_add_f32 v[96:97], v[96:97], v[98:99]
	s_waitcnt lgkmcnt(8)
	v_pk_add_f32 v[100:101], v[100:101], v[102:103]
	s_waitcnt lgkmcnt(6)
	v_pk_add_f32 v[104:105], v[104:105], v[106:107]
	s_waitcnt lgkmcnt(4)
	v_pk_add_f32 v[116:117], v[116:117], v[118:119]
	s_waitcnt lgkmcnt(2)
	v_pk_add_f32 v[68:69], v[68:69], v[124:125]
	s_waitcnt lgkmcnt(0)
	v_pk_add_f32 v[124:125], v[122:123], v[126:127]
	ds_bpermute_b32 v4, v12, v2
	ds_bpermute_b32 v5, v12, v3
	ds_bpermute_b32 v8, v12, v6
	ds_bpermute_b32 v9, v12, v7
	ds_bpermute_b32 v70, v12, v64
	ds_bpermute_b32 v71, v12, v65
	ds_bpermute_b32 v76, v12, v72
	ds_bpermute_b32 v77, v12, v73
	ds_bpermute_b32 v82, v12, v78
	ds_bpermute_b32 v83, v12, v79
	ds_bpermute_b32 v86, v12, v84
	ds_bpermute_b32 v87, v12, v85
	ds_bpermute_b32 v90, v12, v88
	ds_bpermute_b32 v91, v12, v89
	ds_bpermute_b32 v94, v12, v92
	ds_bpermute_b32 v95, v12, v93
	ds_bpermute_b32 v98, v12, v96
	ds_bpermute_b32 v99, v12, v97
	ds_bpermute_b32 v102, v12, v100
	ds_bpermute_b32 v103, v12, v101
	ds_bpermute_b32 v106, v12, v104
	ds_bpermute_b32 v107, v12, v105
	ds_bpermute_b32 v110, v12, v108
	ds_bpermute_b32 v111, v12, v109
	ds_bpermute_b32 v114, v12, v112
	ds_bpermute_b32 v115, v12, v113
	ds_bpermute_b32 v118, v12, v116
	ds_bpermute_b32 v119, v12, v117
	ds_bpermute_b32 v120, v12, v74
	ds_bpermute_b32 v121, v12, v75
	ds_bpermute_b32 v66, v12, v80
	ds_bpermute_b32 v67, v12, v81
	ds_bpermute_b32 v122, v12, v68
	ds_bpermute_b32 v123, v12, v69
	ds_bpermute_b32 v126, v12, v124
	ds_bpermute_b32 v127, v12, v125
	v_and_b32_e32 v12, 63, v55
	v_cmp_gt_u32_e32 vcc, 8, v12
	s_and_saveexec_b64 s[10:11], vcc
	s_cbranch_execz .LBB0_47
	v_lshrrev_b32_e32 v140, 6, v55
	s_waitcnt lgkmcnt(14)
	v_pk_add_f32 v[4:5], v[2:3], v[4:5]
	v_lshlrev_b32_e32 v2, 4, v12
	v_mul_lo_u32 v3, v140, s73
	v_pk_add_f32 v[6:7], v[6:7], v[8:9]
	v_add3_u32 v2, 0, v2, v3
	s_waitcnt lgkmcnt(0)
	v_pk_add_f32 v[124:125], v[124:125], v[126:127]
	v_pk_add_f32 v[122:123], v[68:69], v[122:123]
	v_pk_add_f32 v[68:69], v[80:81], v[66:67]
	v_pk_add_f32 v[66:67], v[74:75], v[120:121]
	v_pk_add_f32 v[116:117], v[116:117], v[118:119]
	v_pk_add_f32 v[114:115], v[112:113], v[114:115]
	v_pk_add_f32 v[108:109], v[108:109], v[110:111]
	v_pk_add_f32 v[106:107], v[104:105], v[106:107]
	v_pk_add_f32 v[100:101], v[100:101], v[102:103]
	v_pk_add_f32 v[98:99], v[96:97], v[98:99]
	v_pk_add_f32 v[92:93], v[92:93], v[94:95]
	v_pk_add_f32 v[90:91], v[88:89], v[90:91]
	v_pk_add_f32 v[80:81], v[84:85], v[86:87]
	v_pk_add_f32 v[78:79], v[78:79], v[82:83]
	v_pk_add_f32 v[72:73], v[72:73], v[76:77]
	v_pk_add_f32 v[70:71], v[64:65], v[70:71]
	ds_write_b128 v2, v[4:7] offset:36864
	ds_write_b128 v2, v[70:73] offset:36992
	ds_write_b128 v2, v[78:81] offset:37120
	ds_write_b128 v2, v[90:93] offset:37248
	ds_write_b128 v2, v[98:101] offset:37376
	ds_write_b128 v2, v[106:109] offset:37504
	ds_write_b128 v2, v[114:117] offset:37632
	ds_write_b128 v2, v[66:69] offset:37760
	ds_write_b128 v2, v[122:125] offset:37888
